# scan23 specialization + 8B pad so later code keeps its 256B placement
# speedup vs baseline: 1.0007x; 1.0007x over previous
.Lscan23_587:
	s_andn2_saveexec_b64 s[34:35], s[34:35]
	v_lshl_add_u64 v[122:123], v[124:125], 1, v[154:155]
	v_lshl_add_u64 v[126:127], v[122:123], 0, 16
	s_or_b64 exec, exec, s[34:35]
	global_load_dwordx4 v[122:125], v[122:123], off
	s_nop 0
	global_load_dwordx4 v[126:129], v[126:127], off
	v_cvt_pk_bf16_f32 v130, v2, v3
	v_cvt_pk_bf16_f32 v131, v4, v5
	v_cvt_pk_bf16_f32 v132, v6, v7
	v_cvt_pk_bf16_f32 v133, v8, v9
	ds_write2_b64 v171, v[130:131], v[132:133] offset1:2
	v_cvt_pk_bf16_f32 v130, v10, v11
	v_cvt_pk_bf16_f32 v131, v12, v13
	v_cvt_pk_bf16_f32 v132, v14, v15
	v_cvt_pk_bf16_f32 v133, v16, v17
	ds_write2_b64 v171, v[130:131], v[132:133] offset0:4 offset1:6
	s_and_saveexec_b64 s[34:35], s[2:3]
	s_cbranch_execz .Lscan23_570
	v_add_co_u32_e32 v130, vcc, 0x2010000, v164
	v_cvt_pk_bf16_f32 v18, v18, s0
	s_nop 0
	v_addc_co_u32_e32 v131, vcc, 0, v165, vcc
	global_store_short v[130:131], v18, off
	v_cvt_pk_bf16_f32 v18, v19, s0
	global_store_short v[130:131], v18, off offset:1024
	v_cvt_pk_bf16_f32 v18, v20, s0
	global_store_short v[130:131], v18, off offset:2048
	v_cvt_pk_bf16_f32 v18, v21, s0
	global_store_short v[130:131], v18, off offset:3072
	v_add_co_u32_e32 v18, vcc, s43, v164
	v_cvt_pk_bf16_f32 v20, v22, s0
	s_nop 0
	v_addc_co_u32_e32 v19, vcc, 0, v165, vcc
	global_store_short v[18:19], v20, off
	v_cvt_pk_bf16_f32 v20, v23, s0
	global_store_short v[18:19], v20, off offset:1024
	v_cvt_pk_bf16_f32 v20, v24, s0
	global_store_short v[18:19], v20, off offset:2048
	v_cvt_pk_bf16_f32 v20, v25, s0
	global_store_short v[18:19], v20, off offset:3072
	v_add_co_u32_e32 v18, vcc, s46, v164
	v_cvt_pk_bf16_f32 v20, v26, s0
	s_nop 0
	v_addc_co_u32_e32 v19, vcc, 0, v165, vcc
	global_store_short v[18:19], v20, off
	v_cvt_pk_bf16_f32 v20, v27, s0
	global_store_short v[18:19], v20, off offset:1024
	v_cvt_pk_bf16_f32 v20, v28, s0
	global_store_short v[18:19], v20, off offset:2048
	v_cvt_pk_bf16_f32 v20, v29, s0
	global_store_short v[18:19], v20, off offset:3072
	v_add_co_u32_e32 v18, vcc, 0x2016000, v164
	v_cvt_pk_bf16_f32 v20, v30, s0
	s_nop 0
	v_addc_co_u32_e32 v19, vcc, 0, v165, vcc
	global_store_short v[18:19], v20, off
	v_cvt_pk_bf16_f32 v20, v31, s0
	global_store_short v[18:19], v20, off offset:1024
	v_cvt_pk_bf16_f32 v20, v32, s0
	global_store_short v[18:19], v20, off offset:2048
	v_cvt_pk_bf16_f32 v20, v33, s0
	global_store_short v[18:19], v20, off offset:3072
	s_branch .Lscan23_570
	s_nop 0
	s_nop 0
